# attention tile loops: next K/V tile global loads issued before the staging barrier instead of after it
# speedup vs baseline: 1.0031x; 1.0031x over previous
; template <int TYPE>
; DI void attn_item(const Params& p, int layer, int head, int qt, int dil, int res, int chunk, char* smem) {
;     ...
;     __syncthreads();
;     if (TYPE == 2) {
;       if ((sflag[0] & sflag[1] & sflag[2] & sflag[3] & sflag[4] & sflag[5] & sflag[6] & sflag[7]) != 0) break;
;     }
;     *(uint4*)(sK + swz(kkey0, kchunk)) = kreg0;
;     ...
;     ATT_VSTORE(vreg0, vdc0)
;     __syncthreads();
;     ATT_PREFETCH((kt > kt_lo) ? kt - 1 : kt);
;     ...
;         const float base = -slope * (float)db - cref;
;         const bool msk = (TYPE == 0) ? true : (__builtin_amdgcn_readfirstlane((Ks + 31 > wq0) ? 1 : 0) != 0);
;         if (msk) {
; #pragma unroll
;           for (int i = 0; i < 16; ++i) {
;             const int ci = (i & 3) + 8 * (i >> 2);
;             const int dist = db - ci;
;             s1[i] = (dist >= 0 && dist <= wlim) ? fmaf(slope, (float)ci, base) : -1e30f;
.LBB0_202:
	v_cmp_gt_i32_e32 vcc, v133, v152
	s_barrier
	s_nop 0
	v_subbrev_co_u32_e32 v0, vcc, 0, v133, vcc
	v_lshlrev_b32_e32 v0, 6, v0
	v_add_u32_e32 v66, v0, v137
	v_or_b32_e32 v0, v0, v177
	v_mad_i64_i32 v[66:67], s[4:5], v66, s85, v[154:155]
	s_waitcnt vmcnt(0)
	ds_write_b128 v186, v[118:121]
	ds_write_b16 v187, v114 offset:8192
	ds_write_b16_d16_hi v187, v114 offset:8320
	ds_write_b16 v188, v115 offset:8192
	ds_write_b16_d16_hi v189, v115 offset:8192
	ds_write_b16 v190, v116 offset:8192
	ds_write_b16_d16_hi v191, v116 offset:8192
	ds_write_b16 v192, v117 offset:8192
	ds_write_b16_d16_hi v193, v117 offset:8192
	v_mad_i64_i32 v[68:69], s[4:5], v0, s85, v[156:157]
	global_load_dwordx4 v[118:121], v[66:67], off
	global_load_dwordx4 v[114:117], v[68:69], off
	s_waitcnt lgkmcnt(0)
	s_barrier
	v_cmp_le_i32_e64 s[4:5], v133, v152
	v_add_u32_e32 v0, 32, v139
	v_cmp_le_i32_e32 vcc, v0, v141
	s_and_saveexec_b64 s[76:77], vcc
	s_cbranch_execz .LBB0_208
	v_subrev_u32_e32 v82, 32, v185
	v_add_u32_e32 v66, 63, v139
	v_cvt_f32_i32_e32 v0, v82
	v_cmp_gt_i32_e32 vcc, v66, v176
	s_mov_b64 s[78:79], -1
	v_fma_f32 v0, -v146, v0, -v135
	v_cndmask_b32_e64 v66, 0, 1, vcc
	v_add_f32_e32 v67, v146, v0
	v_readfirstlane_b32 s10, v66
	s_bitcmp1_b32 s10, 0
	s_cselect_b64 s[96:97], -1, 0
	s_and_b64 vcc, exec, s[96:97]
	v_fma_f32 v66, 0, v146, v0
	s_cbranch_vccnz .LBB0_205
	v_pk_fma_f32 v[68:69], v[146:147], s[54:55], v[0:1] op_sel_hi:[1,1,0]
	v_pk_fma_f32 v[70:71], v[146:147], s[56:57], v[0:1] op_sel_hi:[1,1,0]
	v_pk_fma_f32 v[72:73], v[146:147], s[58:59], v[0:1] op_sel_hi:[1,1,0]
	v_pk_fma_f32 v[74:75], v[146:147], s[60:61], v[0:1] op_sel_hi:[1,1,0]
	v_pk_fma_f32 v[76:77], v[146:147], s[62:63], v[0:1] op_sel_hi:[1,1,0]
	v_pk_fma_f32 v[78:79], v[146:147], s[52:53], v[0:1] op_sel_hi:[1,1,0]
	v_pk_fma_f32 v[80:81], v[146:147], s[64:65], v[0:1] op_sel_hi:[1,1,0]
	s_mov_b64 s[78:79], 0

; DI float ex2(float x) { return __builtin_amdgcn_exp2f(x); }
; DI float lg2(float x) { return __builtin_amdgcn_logf(x); }
; template <int TYPE>
; DI void attn_item(const Params& p, int layer, int head, int qt, int dil, int res, int chunk, char* smem) {
;     ...
;     __syncthreads();
;     if (TYPE == 2) {
;       if ((sflag[0] & sflag[1] & sflag[2] & sflag[3] & sflag[4] & sflag[5] & sflag[6] & sflag[7]) != 0) break;
;     }
;     *(uint4*)(sK + swz(kkey0, kchunk)) = kreg0;
;     ...
;     ATT_VSTORE(vreg0, vdc0)
;     __syncthreads();
;     ATT_PREFETCH((kt > kt_lo) ? kt - 1 : kt);
;     ...
;         for (int i = 0; i < 16; ++i) {
;           const int ci = (i & 3) + 8 * (i >> 2);
;           const float z = s1[i];
;           const float t = lg2(1.f + ex2(-fabsf(z)));
;           float f = -(fmaxf(z, 0.f) + t);
;           float g = fminf(z, 0.f) - t;
;           if (masked) {
;             const bool ok = (db - ci) > 0;
;             f = ok ? f : 0.f;
;             g = ok ? g : -1e30f;
;           }
;           lf[i] = f;
;           lsg[i] = g;
;           tsum += f;
;         }
.LBB0_234:
	v_mov_b32_e32 v105, v101
	s_waitcnt lgkmcnt(0)
	s_barrier
	ds_read_b32 v0, v100
	ds_read_b32 v34, v104
	v_mov_b32_e32 v107, v101
	v_mov_b32_e32 v109, v101
	ds_read_b32 v35, v106
	ds_read_b32 v36, v108
	v_mov_b32_e32 v111, v101
	v_mov_b32_e32 v113, v101
	ds_read_b32 v37, v110
	ds_read_b32 v38, v112
	v_mov_b32_e32 v115, v101
	v_mov_b32_e32 v117, v101
	ds_read_b32 v39, v114
	ds_read_b32 v40, v116
	s_waitcnt vmcnt(0)
	s_or_b64 s[58:59], s[58:59], exec
	s_waitcnt lgkmcnt(0)
	v_and_b32_e32 v0, v34, v0
	v_bitop3_b32 v0, v0, v36, v35 bitop3:0x80
	v_bitop3_b32 v0, v0, v38, v37 bitop3:0x80
	v_bitop3_b32 v0, v0, v40, v39 bitop3:0x80
	v_cmp_eq_u32_e64 s[0:1], 0, v0
	s_and_saveexec_b64 s[60:61], s[0:1]
	s_cbranch_execz .LBB0_233
	v_min_u32_e32 v0, 1, v132
	v_lshlrev_b32_e32 v0, 6, v0
	v_add_u32_e32 v34, v137, v99
	v_sub_u32_e32 v34, v34, v0
	v_add_u32_e32 v35, v136, v99
	v_sub_u32_e32 v0, v35, v0
	v_mad_i64_i32 v[34:35], s[0:1], v34, s67, v[120:121]
	ds_write_b128 v139, v[74:77]
	ds_write_b16 v140, v70 offset:8192
	ds_write_b16_d16_hi v140, v70 offset:8320
	ds_write_b16 v141, v71 offset:8192
	ds_write_b16_d16_hi v142, v71 offset:8192
	ds_write_b16 v143, v72 offset:8192
	ds_write_b16_d16_hi v144, v72 offset:8192
	ds_write_b16 v145, v73 offset:8192
	ds_write_b16_d16_hi v146, v73 offset:8192
	v_mad_u64_u32 v[36:37], s[0:1], v0, s67, v[122:123]
	global_load_dwordx4 v[74:77], v[34:35], off
	global_load_dwordx4 v[70:73], v[36:37], off
	s_waitcnt lgkmcnt(0)
	s_barrier
	v_add_u32_e32 v0, 0x3fe0, v99
	v_cmp_lt_i32_e64 s[0:1], v0, v133
	s_and_saveexec_b64 s[62:63], s[0:1]
	s_cbranch_execz .LBB0_239
	ds_read_b32 v0, v124
	s_waitcnt lgkmcnt(0)
	v_cmp_eq_u32_e64 s[0:1], 0, v0
	s_and_saveexec_b64 s[64:65], s[0:1]
	s_cbranch_execz .LBB0_238
	ds_read_b128 v[34:37], v147 offset:4096
	ds_read_b128 v[82:85], v148 offset:4096
	v_add_u32_e32 v0, 0x3fff, v99
	v_add_u32_e32 v105, 27, v135
	v_add_u32_e32 v107, 26, v135
	s_waitcnt lgkmcnt(1)
	v_mfma_f32_32x32x16_bf16 v[34:49], v[34:37], v[50:53], 0
	v_cmp_lt_i32_e64 s[2:3], v0, v130
	v_cmp_lt_i32_e64 s[0:1], 0, v105
	v_cmp_lt_i32_e64 s[4:5], 0, v107
	v_add_u32_e32 v109, 25, v135
	v_cmp_lt_i32_e64 s[6:7], 0, v109
	s_or_b64 s[0:1], s[2:3], s[0:1]
	s_waitcnt lgkmcnt(0)
	v_mfma_f32_32x32x16_bf16 v[34:49], v[82:85], v[54:57], v[34:49]
	ds_read_b128 v[152:155], v149 offset:4096
	ds_read_b128 v[94:97], v149 offset:8192
	ds_read_b128 v[168:171], v150 offset:4096
	ds_read_b128 v[90:93], v149 offset:12288
	ds_read_b128 v[86:89], v150 offset:8192
	ds_read_b128 v[82:85], v150 offset:12288
	s_waitcnt lgkmcnt(5)
	v_mfma_f32_32x32x16_bf16 v[34:49], v[152:155], v[58:61], v[34:49]
	s_waitcnt lgkmcnt(3)
	v_mfma_f32_32x32x16_bf16 v[34:49], v[168:171], v[62:65], v[34:49]
	s_nop 11
	v_exp_f32_e64 v0, -|v34|
	v_exp_f32_e64 v105, -|v35|
	v_exp_f32_e64 v107, -|v36|
	v_max_f32_e32 v34, v34, v34
	v_add_f32_e32 v0, 1.0, v0
	v_add_f32_e32 v105, 1.0, v105
	v_log_f32_e32 v0, v0
	v_add_f32_e32 v107, 1.0, v107
	v_log_f32_e32 v105, v105
	v_log_f32_e32 v107, v107
	v_exp_f32_e64 v109, -|v37|
	v_max_f32_e32 v35, v35, v35
	v_max_f32_e32 v36, v36, v36
	v_max_f32_e32 v111, 0, v34
	v_min_f32_e32 v34, 0, v34
	v_max_f32_e32 v113, 0, v35
	v_min_f32_e32 v35, 0, v35
	v_max_f32_e32 v115, 0, v36
	v_min_f32_e32 v36, 0, v36
	v_add_f32_e32 v111, v111, v0
	v_sub_f32_e32 v0, v34, v0
	v_add_f32_e32 v34, v113, v105
	v_sub_f32_e32 v35, v35, v105
	v_add_f32_e32 v105, v115, v107
	v_sub_f32_e32 v36, v36, v107
	v_cndmask_b32_e64 v107, 0, -v111, s[0:1]
	v_cndmask_b32_e64 v0, v128, v0, s[0:1]
	s_or_b64 s[0:1], s[2:3], s[4:5]
	v_cndmask_b32_e64 v113, v128, v35, s[0:1]
	v_add_f32_e32 v35, 1.0, v109
	v_log_f32_e32 v35, v35
	v_cndmask_b32_e64 v111, 0, -v34, s[0:1]
	s_or_b64 s[0:1], s[2:3], s[6:7]
	v_cndmask_b32_e64 v115, v128, v36, s[0:1]
	v_max_f32_e32 v36, v37, v37
	v_max_f32_e32 v37, 0, v36
	v_min_f32_e32 v36, 0, v36
	v_add_f32_e32 v37, v37, v35
	v_sub_f32_e32 v35, v36, v35
	v_add_u32_e32 v36, 24, v135
	v_cndmask_b32_e64 v105, 0, -v105, s[0:1]
	v_cmp_lt_i32_e64 s[0:1], 0, v36
	v_exp_f32_e64 v36, -|v38|
	s_or_b64 s[0:1], s[2:3], s[0:1]
	v_cndmask_b32_e64 v109, v128, v35, s[0:1]
	v_cndmask_b32_e64 v37, 0, -v37, s[0:1]
	v_add_f32_e32 v35, 1.0, v36
	v_log_f32_e32 v35, v35
	v_max_f32_e32 v36, v38, v38
	v_max_f32_e32 v38, 0, v36
	v_min_f32_e32 v36, 0, v36
	v_add_f32_e32 v38, v38, v35
	v_sub_f32_e32 v35, v36, v35
	v_add_u32_e32 v36, 19, v135
	v_cmp_lt_i32_e64 s[0:1], 0, v36
	v_exp_f32_e64 v36, -|v39|
	s_or_b64 s[0:1], s[2:3], s[0:1]
	v_cndmask_b32_e64 v117, v128, v35, s[0:1]
	v_cndmask_b32_e64 v38, 0, -v38, s[0:1]
	v_add_f32_e32 v35, 1.0, v36
	v_log_f32_e32 v35, v35
	v_max_f32_e32 v36, v39, v39
	v_max_f32_e32 v39, 0, v36
	v_min_f32_e32 v36, 0, v36
	v_add_f32_e32 v39, v39, v35
	v_sub_f32_e32 v35, v36, v35
	v_add_u32_e32 v36, 18, v135
	v_cmp_lt_i32_e64 s[0:1], 0, v36
	v_exp_f32_e64 v36, -|v40|
	s_or_b64 s[0:1], s[2:3], s[0:1]
	v_cndmask_b32_e64 v151, v128, v35, s[0:1]
	v_cndmask_b32_e64 v39, 0, -v39, s[0:1]
	v_add_f32_e32 v35, 1.0, v36
	v_log_f32_e32 v35, v35
	v_max_f32_e32 v36, v40, v40
	v_max_f32_e32 v40, 0, v36
	v_min_f32_e32 v36, 0, v36
	v_add_f32_e32 v40, v40, v35
	v_sub_f32_e32 v35, v36, v35
	v_add_u32_e32 v36, 17, v135
	v_cmp_lt_i32_e64 s[0:1], 0, v36
	v_exp_f32_e64 v36, -|v41|
	s_or_b64 s[0:1], s[2:3], s[0:1]
	v_cndmask_b32_e64 v156, v128, v35, s[0:1]
	v_cndmask_b32_e64 v40, 0, -v40, s[0:1]
	v_add_f32_e32 v35, 1.0, v36
	v_log_f32_e32 v35, v35
	v_max_f32_e32 v36, v41, v41
	v_max_f32_e32 v41, 0, v36
	v_min_f32_e32 v36, 0, v36
	v_add_f32_e32 v41, v41, v35
	v_sub_f32_e32 v35, v36, v35
	v_add_u32_e32 v36, 16, v135
	v_cmp_lt_i32_e64 s[0:1], 0, v36
	v_exp_f32_e64 v36, -|v42|
; DI float bflo(unsigned u) { return __uint_as_float(u << 16); }
; DI float bfhi(unsigned u) { return __uint_as_float(u & 0xffff0000u); }
; DI f32x16 mfma32(bf16x8 a, bf16x8 b, f32x16 c) { return __builtin_amdgcn_mfma_f32_32x32x16_bf16(a, b, c, 0, 0, 0); }
; DI float ex2(float x) { return __builtin_amdgcn_exp2f(x); }
; DI float lg2(float x) { return __builtin_amdgcn_logf(x); }
; template <int TYPE>
; DI void attn_item(const Params& p, int layer, int head, int qt, int dil, int res, int chunk, char* smem) {
;     ...
;         for (int i = 0; i < 16; ++i) {
;           const int ci = (i & 3) + 8 * (i >> 2);
;           const float z = s1[i];
;           const float t = lg2(1.f + ex2(-fabsf(z)));
;           float f = -(fmaxf(z, 0.f) + t);
;           float g = fminf(z, 0.f) - t;
;           if (masked) {
;             const bool ok = (db - ci) > 0;
;             f = ok ? f : 0.f;
;             g = ok ? g : -1e30f;
;           }
;           lf[i] = f;
;           lsg[i] = g;
;           tsum += f;
;         }
;         unsigned hi[8], lo[8];
; #pragma unroll
;         for (int i = 0; i < 8; ++i) {
;           hi[i] = pack2(lf[2 * i], lf[2 * i + 1]);
;           lo[i] = pack2(lf[2 * i] - bflo(hi[i]), lf[2 * i + 1] - bfhi(hi[i]));
;         }
;         f32x16 aft;
; #pragma unroll
;         for (int i = 0; i < 16; ++i) aft[i] = 0.f;
;         aft = mfma32(Tm0, mk8(hi[0], hi[1], hi[2], hi[3]), aft);
;         aft = mfma32(Tm1, mk8(hi[4], hi[5], hi[6], hi[7]), aft);
;         aft = mfma32(Tm0, mk8(lo[0], lo[1], lo[2], lo[3]), aft);
;         aft = mfma32(Tm1, mk8(lo[4], lo[5], lo[6], lo[7]), aft);
;         float w[16];
; #pragma unroll
;         for (int i = 0; i < 16; ++i) w[i] = ex2(lsg[i] + aft[i] + carry);
;         tsum += __shfl_xor(tsum, 32);
;         carry += tsum;
;         bf16x8 pk0 = mk8(pack2(w[0], w[1]), pack2(w[2], w[3]), pack2(w[4], w[5]), pack2(w[6], w[7]));
;         bf16x8 pk1 = mk8(pack2(w[8], w[9]), pack2(w[10], w[11]), pack2(w[12], w[13]), pack2(w[14], w[15]));
;         O1a = mfma32(vf[0][0], pk0, O1a);
;         O1b = mfma32(vf[0][1], pk0, O1b);
;         O1a = mfma32(vf[1][0], pk1, O1a);
;         O1b = mfma32(vf[1][1], pk1, O1b);
	s_or_b64 s[0:1], s[2:3], s[0:1]
	v_cndmask_b32_e64 v157, v128, v35, s[0:1]
	v_cndmask_b32_e64 v41, 0, -v41, s[0:1]
	v_add_f32_e32 v35, 1.0, v36
	v_log_f32_e32 v35, v35
	v_max_f32_e32 v36, v42, v42
	v_max_f32_e32 v42, 0, v36
	v_min_f32_e32 v36, 0, v36
	v_add_f32_e32 v42, v42, v35
	v_sub_f32_e32 v35, v36, v35
	v_add_u32_e32 v36, 11, v135
	v_cmp_lt_i32_e64 s[0:1], 0, v36
	v_exp_f32_e64 v36, -|v43|
	s_or_b64 s[0:1], s[2:3], s[0:1]
	v_cndmask_b32_e64 v167, v128, v35, s[0:1]
	v_cndmask_b32_e64 v42, 0, -v42, s[0:1]
	v_add_f32_e32 v35, 1.0, v36
	v_log_f32_e32 v35, v35
	v_max_f32_e32 v36, v43, v43
	v_max_f32_e32 v43, 0, v36
	v_min_f32_e32 v36, 0, v36
	v_add_f32_e32 v43, v43, v35
	v_sub_f32_e32 v35, v36, v35
	v_add_u32_e32 v36, 10, v135
	v_cmp_lt_i32_e64 s[0:1], 0, v36
	v_exp_f32_e64 v36, -|v44|
	s_or_b64 s[0:1], s[2:3], s[0:1]
	v_cndmask_b32_e64 v176, v128, v35, s[0:1]
	v_cndmask_b32_e64 v169, 0, -v43, s[0:1]
	v_add_f32_e32 v35, 1.0, v36
	v_log_f32_e32 v35, v35
	v_max_f32_e32 v36, v44, v44
	v_max_f32_e32 v43, 0, v36
	v_min_f32_e32 v36, 0, v36
	v_add_f32_e32 v43, v43, v35
	v_sub_f32_e32 v35, v36, v35
	v_add_u32_e32 v36, 9, v135
	v_cmp_lt_i32_e64 s[0:1], 0, v36
	v_exp_f32_e64 v36, -|v45|
	s_or_b64 s[0:1], s[2:3], s[0:1]
	v_cndmask_b32_e64 v177, v128, v35, s[0:1]
	v_cndmask_b32_e64 v173, 0, -v43, s[0:1]
	v_add_f32_e32 v35, 1.0, v36
	v_log_f32_e32 v35, v35
	v_max_f32_e32 v36, v45, v45
	v_max_f32_e32 v43, 0, v36
	v_min_f32_e32 v36, 0, v36
	v_add_f32_e32 v43, v43, v35
	v_sub_f32_e32 v35, v36, v35
	v_add_u32_e32 v36, 8, v135
	v_cmp_lt_i32_e64 s[0:1], 0, v36
	v_exp_f32_e64 v36, -|v46|
	s_or_b64 s[0:1], s[2:3], s[0:1]
	v_cndmask_b32_e64 v178, v128, v35, s[0:1]
	v_cndmask_b32_e64 v174, 0, -v43, s[0:1]
	v_add_f32_e32 v35, 1.0, v36
	v_log_f32_e32 v35, v35
	v_max_f32_e32 v36, v46, v46
	v_max_f32_e32 v43, 0, v36
	v_min_f32_e32 v36, 0, v36
	v_add_f32_e32 v43, v43, v35
	v_sub_f32_e32 v35, v36, v35
	v_add_u32_e32 v36, 3, v135
	v_cmp_lt_i32_e64 s[0:1], 0, v36
	v_exp_f32_e64 v36, -|v47|
	s_or_b64 s[0:1], s[2:3], s[0:1]
	v_cndmask_b32_e64 v179, v128, v35, s[0:1]
	v_cndmask_b32_e64 v175, 0, -v43, s[0:1]
	v_add_f32_e32 v35, 1.0, v36
	v_log_f32_e32 v35, v35
	v_max_f32_e32 v36, v47, v47
	v_max_f32_e32 v43, 0, v36
	v_min_f32_e32 v36, 0, v36
	v_add_f32_e32 v43, v43, v35
	v_sub_f32_e32 v35, v36, v35
	v_add_u32_e32 v36, 2, v135
	v_cmp_lt_i32_e64 s[0:1], 0, v36
	v_exp_f32_e64 v36, -|v48|
	s_or_b64 s[0:1], s[2:3], s[0:1]
	v_cndmask_b32_e64 v181, v128, v35, s[0:1]
	v_add_f32_e32 v34, 0, v107
	v_add_f32_e32 v35, 1.0, v36
	v_log_f32_e32 v35, v35
	v_add_f32_e32 v34, v111, v34
	v_max_f32_e32 v36, v48, v48
	v_add_f32_e32 v34, v105, v34
	v_cndmask_b32_e64 v180, 0, -v43, s[0:1]
	v_max_f32_e32 v43, 0, v36
	v_min_f32_e32 v36, 0, v36
	v_add_f32_e32 v34, v37, v34
	v_add_f32_e32 v43, v43, v35
	v_sub_f32_e32 v35, v36, v35
	v_add_u32_e32 v36, 1, v135
	v_add_f32_e32 v34, v38, v34
	v_cmp_lt_i32_e64 s[0:1], 0, v36
	v_exp_f32_e64 v36, -|v49|
	v_add_f32_e32 v34, v39, v34
	v_add_f32_e32 v34, v40, v34
	v_add_f32_e32 v34, v41, v34
	s_or_b64 s[0:1], s[2:3], s[0:1]
	v_add_f32_e32 v34, v42, v34
	v_cndmask_b32_e64 v183, v128, v35, s[0:1]
	v_add_f32_e32 v35, 1.0, v36
	v_add_f32_e32 v34, v169, v34
	v_log_f32_e32 v35, v35
	v_add_f32_e32 v34, v173, v34
	v_add_f32_e32 v34, v174, v34
	v_max_f32_e32 v36, v49, v49
	v_add_f32_e32 v34, v175, v34
	v_cndmask_b32_e64 v182, 0, -v43, s[0:1]
	v_max_f32_e32 v43, 0, v36
	v_cmp_lt_i32_e64 s[0:1], 0, v135
	v_add_f32_e32 v34, v180, v34
	v_add_f32_e32 v43, v43, v35
	s_or_b64 s[0:1], s[2:3], s[0:1]
	v_add_f32_e32 v34, v182, v34
	v_min_f32_e32 v36, 0, v36
	v_cndmask_b32_e64 v184, 0, -v43, s[0:1]
	v_sub_f32_e32 v35, v36, v35
	v_add_f32_e32 v186, v184, v34
	v_cvt_pk_bf16_f32 v34, v107, v111
	v_cndmask_b32_e64 v185, v128, v35, s[0:1]
	v_lshlrev_b32_e32 v35, 16, v34
	v_and_b32_e32 v36, 0xffff0000, v34
	v_sub_f32_e32 v35, v107, v35
	v_sub_f32_e32 v36, v111, v36
	v_cvt_pk_bf16_f32 v152, v35, v36
	v_cvt_pk_bf16_f32 v35, v105, v37
	v_lshlrev_b32_e32 v36, 16, v35
	v_and_b32_e32 v43, 0xffff0000, v35
	v_sub_f32_e32 v36, v105, v36
	v_sub_f32_e32 v37, v37, v43
	v_cvt_pk_bf16_f32 v153, v36, v37
	v_cvt_pk_bf16_f32 v36, v38, v39
	v_lshlrev_b32_e32 v37, 16, v36
	v_sub_f32_e32 v37, v38, v37
	v_and_b32_e32 v38, 0xffff0000, v36
	v_sub_f32_e32 v38, v39, v38
	v_cvt_pk_bf16_f32 v154, v37, v38
	v_cvt_pk_bf16_f32 v37, v40, v41
	v_lshlrev_b32_e32 v38, 16, v37
	v_and_b32_e32 v39, 0xffff0000, v37
	v_sub_f32_e32 v38, v40, v38
	v_sub_f32_e32 v39, v41, v39
	v_cvt_pk_bf16_f32 v168, v42, v169
	v_cvt_pk_bf16_f32 v155, v38, v39
	v_lshlrev_b32_e32 v38, 16, v168
	v_sub_f32_e32 v105, v42, v38
	v_mfma_f32_32x32x16_bf16 v[34:49], v[66:69], v[34:37], 0
	v_and_b32_e32 v107, 0xffff0000, v168
	v_sub_f32_e32 v107, v169, v107
	v_cvt_pk_bf16_f32 v169, v173, v174
	v_cvt_pk_bf16_f32 v170, v175, v180
	v_cvt_pk_bf16_f32 v171, v182, v184
	v_cvt_pk_bf16_f32 v172, v105, v107
	v_lshlrev_b32_e32 v105, 16, v169
	v_mfma_f32_32x32x16_bf16 v[34:49], v[78:81], v[168:171], v[34:49]
	v_and_b32_e32 v107, 0xffff0000, v169
	v_sub_f32_e32 v105, v173, v105
	v_sub_f32_e32 v107, v174, v107
	v_cvt_pk_bf16_f32 v173, v105, v107
	v_lshlrev_b32_e32 v105, 16, v170
	v_and_b32_e32 v107, 0xffff0000, v170
	v_sub_f32_e32 v105, v175, v105
	v_mfma_f32_32x32x16_bf16 v[34:49], v[66:69], v[152:155], v[34:49]
	v_sub_f32_e32 v107, v180, v107
	v_cvt_pk_bf16_f32 v174, v105, v107
	v_lshlrev_b32_e32 v105, 16, v171
	v_and_b32_e32 v107, 0xffff0000, v171
	v_sub_f32_e32 v105, v182, v105
	v_sub_f32_e32 v107, v184, v107
	v_cvt_pk_bf16_f32 v175, v105, v107
	v_cmp_lt_i32_e64 s[0:1], v159, v165
	s_nop 0
	v_mfma_f32_32x32x16_bf16 v[34:49], v[78:81], v[172:175], v[34:49]
	s_nop 11
	v_add_f32_e32 v0, v0, v34
	v_add_f32_e32 v34, v113, v35
	v_add_f32_e32 v35, v115, v36
	v_add_f32_e32 v36, v109, v37
	v_add_f32_e32 v37, v117, v38
	v_add_f32_e32 v38, v151, v39
	v_add_f32_e32 v39, v156, v40
	v_add_f32_e32 v40, v157, v41
	v_add_f32_e32 v0, v138, v0
	v_add_f32_e32 v34, v138, v34
	v_add_f32_e32 v35, v138, v35
	v_add_f32_e32 v36, v138, v36
	v_add_f32_e32 v37, v138, v37
	v_add_f32_e32 v38, v138, v38
	v_add_f32_e32 v39, v138, v39
	v_add_f32_e32 v40, v138, v40
	v_exp_f32_e32 v0, v0
	v_exp_f32_e32 v34, v34
	v_exp_f32_e32 v35, v35
	v_exp_f32_e32 v36, v36
	v_exp_f32_e32 v37, v37
	v_exp_f32_e32 v38, v38
	v_exp_f32_e32 v39, v39
	v_exp_f32_e32 v40, v40
	v_cvt_pk_bf16_f32 v34, v0, v34
	v_cvt_pk_bf16_f32 v35, v35, v36
	v_cvt_pk_bf16_f32 v36, v37, v38
	v_cvt_pk_bf16_f32 v37, v39, v40
	v_add_f32_e32 v41, v167, v42
	v_add_f32_e32 v42, v176, v43
	v_mfma_f32_32x32x16_bf16 v[18:33], v[94:97], v[34:37], v[18:33]
	v_add_f32_e32 v43, v177, v44
	v_add_f32_e32 v44, v178, v45
	v_add_f32_e32 v45, v179, v46
	v_add_f32_e32 v46, v181, v47
	v_add_f32_e32 v38, v183, v48
	v_add_f32_e32 v39, v185, v49
	v_add_f32_e32 v41, v138, v41
	s_waitcnt lgkmcnt(2)
; DI f32x16 mfma32(bf16x8 a, bf16x8 b, f32x16 c) { return __builtin_amdgcn_mfma_f32_32x32x16_bf16(a, b, c, 0, 0, 0); }
; DI float ex2(float x) { return __builtin_amdgcn_exp2f(x); }
; template <int TYPE>
; DI void attn_item(const Params& p, int layer, int head, int qt, int dil, int res, int chunk, char* smem) {
;     ...
;         float w[16];
; #pragma unroll
;         for (int i = 0; i < 16; ++i) w[i] = ex2(lsg[i] + aft[i] + carry);
;         tsum += __shfl_xor(tsum, 32);
;         carry += tsum;
;         bf16x8 pk0 = mk8(pack2(w[0], w[1]), pack2(w[2], w[3]), pack2(w[4], w[5]), pack2(w[6], w[7]));
;         bf16x8 pk1 = mk8(pack2(w[8], w[9]), pack2(w[10], w[11]), pack2(w[12], w[13]), pack2(w[14], w[15]));
;         O1a = mfma32(vf[0][0], pk0, O1a);
;         O1b = mfma32(vf[0][1], pk0, O1b);
;         O1a = mfma32(vf[1][0], pk1, O1a);
;         O1b = mfma32(vf[1][1], pk1, O1b);
	v_mfma_f32_32x32x16_bf16 v[2:17], v[90:93], v[34:37], v[2:17]
	v_add_f32_e32 v42, v138, v42
	v_add_f32_e32 v43, v138, v43
	v_add_f32_e32 v44, v138, v44
	v_add_f32_e32 v45, v138, v45
	v_add_f32_e32 v46, v138, v46
	v_add_f32_e32 v38, v138, v38
	v_add_f32_e32 v39, v138, v39
	v_exp_f32_e32 v41, v41
	v_exp_f32_e32 v42, v42
	v_exp_f32_e32 v43, v43
	v_exp_f32_e32 v44, v44
	v_exp_f32_e32 v45, v45
	v_exp_f32_e32 v0, v46
	v_exp_f32_e32 v38, v38
	v_exp_f32_e32 v39, v39
	v_cndmask_b32_e64 v34, v164, v159, s[0:1]
	v_lshlrev_b32_e32 v40, 2, v34
	v_cvt_pk_bf16_f32 v34, v41, v42
	v_cvt_pk_bf16_f32 v35, v43, v44
	v_cvt_pk_bf16_f32 v36, v45, v0
	v_cvt_pk_bf16_f32 v37, v38, v39
	ds_bpermute_b32 v0, v40, v186
	s_waitcnt lgkmcnt(0)
	v_add_f32_e32 v0, v186, v0
	v_mfma_f32_32x32x16_bf16 v[18:33], v[86:89], v[34:37], v[18:33]
	v_add_f32_e32 v138, v138, v0
	v_mfma_f32_32x32x16_bf16 v[2:17], v[82:85], v[34:37], v[2:17]

; DI f32x16 mfma32(bf16x8 a, bf16x8 b, f32x16 c) { return __builtin_amdgcn_mfma_f32_32x32x16_bf16(a, b, c, 0, 0, 0); }
; template <int TYPE>
; DI void attn_item(const Params& p, int layer, int head, int qt, int dil, int res, int chunk, char* smem) {
;     ...
;     __syncthreads();
;     if (TYPE == 2) {
;       if ((sflag[0] & sflag[1] & sflag[2] & sflag[3] & sflag[4] & sflag[5] & sflag[6] & sflag[7]) != 0) break;
;     }
;     *(uint4*)(sK + swz(kkey0, kchunk)) = kreg0;
;     ...
;     ATT_VSTORE(vreg0, vdc0)
;     __syncthreads();
;     ATT_PREFETCH((kt > kt_lo) ? kt - 1 : kt);
;     ...
;         const float base = -slope * (float)db - cref;
;         const bool msk = (TYPE == 0) ? true : (__builtin_amdgcn_readfirstlane((Ks + 31 > wq0) ? 1 : 0) != 0);
;         if (msk) {
; #pragma unroll
;           for (int i = 0; i < 16; ++i) {
;             const int ci = (i & 3) + 8 * (i >> 2);
;             const int dist = db - ci;
;             s1[i] = (dist >= 0 && dist <= wlim) ? fmaf(slope, (float)ci, base) : -1e30f;
;             s2[i] = s1[i];
;           }
;         } else {
; #pragma unroll
;           for (int i = 0; i < 16; ++i) {
;             const int ci = (i & 3) + 8 * (i >> 2);
;             s1[i] = fmaf(slope, (float)ci, base);
;             s2[i] = s1[i];
;           }
;         }
;       }
;       {
;         bf16x8 kf[4];
; #pragma unroll
;         for (int ks = 0; ks < 4; ++ks) kf[ks] = *(const bf16x8*)(sK + swz(32 * sub + ql, 2 * ks + h));
;         if (TYPE == 1) {
;           s1 = mfma32(kf[0], qf[0], s1);
;           s1 = mfma32(kf[1], qf[1], s1);
;           s2 = mfma32(kf[2], qf[2], s2);
;           s2 = mfma32(kf[3], qf[3], s2);
;         } else {
; #pragma unroll
;           for (int ks = 0; ks < 4; ++ks) s1 = mfma32(kf[ks], qf[ks], s1);
;         }
;       }
;       bf16x8 vf[2][2];
; #pragma unroll
;       for (int s = 0; s < 2; ++s)
; #pragma unroll
;         for (int dt = 0; dt < 2; ++dt) vf[s][dt] = *(const bf16x8*)(sV + swz(32 * dt + ql, 4 * sub + 2 * s + h));
;       if (TYPE == 0 || TYPE == 1) {
;         const bool masked = (TYPE == 0) ? true : (Ks + 31 > wq0);
;         bf16x8 pk0, pk1;
;         fx_step(s1, l1, db, masked, wlim, pk0, pk1);
;         O1a = mfma32(vf[0][0], pk0, O1a);
;         O1b = mfma32(vf[0][1], pk0, O1b);
;         O1a = mfma32(vf[1][0], pk1, O1a);
;         O1b = mfma32(vf[1][1], pk1, O1b);
.LBB0_256:
	v_cmp_gt_i32_e32 vcc, v99, v100
	s_barrier
	s_nop 0
	v_subbrev_co_u32_e32 v32, vcc, 0, v99, vcc
	v_lshlrev_b32_e32 v34, 6, v32
	v_add_u32_e32 v32, v34, v101
	v_ashrrev_i32_e32 v33, 31, v32
	v_or_b32_e32 v34, v34, v75
	v_lshlrev_b64 v[32:33], v79, v[32:33]
	v_ashrrev_i32_e32 v35, 31, v34
	v_lshl_add_u64 v[32:33], v[32:33], 0, v[86:87]
	v_lshlrev_b64 v[34:35], v79, v[34:35]
	v_lshl_add_u64 v[34:35], v[34:35], 0, v[86:87]
	v_mad_u64_u32 v[36:37], s[0:1], v32, s71, v[88:89]
	v_mad_i32_i24 v37, v33, s71, v37
	v_mad_u64_u32 v[32:33], s[0:1], v34, s71, v[90:91]
	s_waitcnt vmcnt(0)
	ds_write_b128 v108, v[68:71]
	ds_write_b16 v109, v64 offset:8192
	ds_write_b16_d16_hi v109, v64 offset:8320
	ds_write_b16 v110, v65 offset:8192
	ds_write_b16_d16_hi v111, v65 offset:8192
	ds_write_b16 v112, v66 offset:8192
	ds_write_b16_d16_hi v113, v66 offset:8192
	ds_write_b16 v114, v67 offset:8192
	ds_write_b16_d16_hi v115, v67 offset:8192
	v_mad_i32_i24 v33, v35, s71, v33
	global_load_dwordx4 v[68:71], v[36:37], off
	global_load_dwordx4 v[64:67], v[32:33], off
	s_waitcnt lgkmcnt(0)
	s_barrier
	v_cmp_le_i32_e32 vcc, v99, v100
	v_add_u32_e32 v32, 1, v107
	v_cmp_le_i32_e64 s[0:1], v32, v102
	v_add_u32_e32 v32, 32, v107
	v_cmp_ge_i32_e64 s[2:3], v32, v103
	s_and_b64 s[0:1], s[0:1], s[2:3]
	s_and_saveexec_b64 s[2:3], s[0:1]
	s_cbranch_execz .LBB0_258
	v_add_u32_e32 v32, 1, v106
	v_cvt_f32_i32_e32 v33, v32
	v_cmp_gt_u32_e64 s[0:1], s76, v32
	v_add_u32_e32 v36, -2, v106
	v_add_u32_e32 v37, -1, v106
	v_fma_f32 v46, -v92, v33, -v105
	v_fma_f32 v33, 0, v92, v46
	v_add_f32_e32 v34, v92, v46
	v_cndmask_b32_e64 v32, v98, v33, s[0:1]
	v_cmp_gt_u32_e64 s[0:1], s76, v106
	v_add_u32_e32 v38, -8, v106
	v_add_u32_e32 v39, -7, v106
	v_cndmask_b32_e64 v33, v98, v34, s[0:1]
	v_pk_fma_f32 v[34:35], v[92:93], s[34:35], v[46:47] op_sel_hi:[1,1,0]
	v_cmp_gt_u32_e64 s[0:1], s76, v36
	v_add_u32_e32 v40, -10, v106
	v_add_u32_e32 v41, -9, v106
	v_cndmask_b32_e64 v35, v98, v35, s[0:1]
	v_cmp_gt_u32_e64 s[0:1], s76, v37
	v_pk_fma_f32 v[36:37], v[92:93], s[36:37], v[46:47] op_sel_hi:[1,1,0]
	v_add_u32_e32 v42, -16, v106
	v_cndmask_b32_e64 v34, v98, v34, s[0:1]
	v_cmp_gt_u32_e64 s[0:1], s76, v38
	v_add_u32_e32 v43, -15, v106
	v_subrev_u32_e32 v44, 18, v106
	v_cndmask_b32_e64 v37, v98, v37, s[0:1]
	v_cmp_gt_u32_e64 s[0:1], s76, v39
	v_pk_fma_f32 v[38:39], v[92:93], s[52:53], v[46:47] op_sel_hi:[1,1,0]
	v_subrev_u32_e32 v45, 17, v106
	v_cndmask_b32_e64 v36, v98, v36, s[0:1]
	v_cmp_gt_u32_e64 s[0:1], s76, v40
	v_subrev_u32_e32 v120, 23, v106
	v_subrev_u32_e32 v124, 26, v106
	v_cndmask_b32_e64 v39, v98, v39, s[0:1]
	v_cmp_gt_u32_e64 s[0:1], s76, v41
	v_pk_fma_f32 v[40:41], v[92:93], s[54:55], v[46:47] op_sel_hi:[1,1,0]
	v_subrev_u32_e32 v125, 25, v106
	v_cndmask_b32_e64 v38, v98, v38, s[0:1]
	v_cmp_gt_u32_e64 s[0:1], s76, v42
	s_nop 1
	v_cndmask_b32_e64 v41, v98, v41, s[0:1]
	v_cmp_gt_u32_e64 s[0:1], s76, v43
	v_pk_fma_f32 v[42:43], v[92:93], s[56:57], v[46:47] op_sel_hi:[1,1,0]
	v_subrev_u32_e32 v47, 24, v106
	v_cndmask_b32_e64 v40, v98, v40, s[0:1]
	v_cmp_gt_u32_e64 s[0:1], s76, v44
	s_nop 1
	v_cndmask_b32_e64 v43, v98, v43, s[0:1]
	v_cmp_gt_u32_e64 s[0:1], s76, v45
	v_pk_fma_f32 v[44:45], v[92:93], s[58:59], v[46:47] op_sel_hi:[1,1,0]
	s_nop 0
	v_cndmask_b32_e64 v42, v98, v42, s[0:1]
	v_cmp_gt_u32_e64 s[0:1], s76, v47
	v_pk_fma_f32 v[46:47], v[92:93], s[60:61], v[46:47] op_sel_hi:[1,1,0]
	s_nop 0
	v_cndmask_b32_e64 v45, v98, v45, s[0:1]
	v_cmp_gt_u32_e64 s[0:1], s76, v120
	ds_read_b128 v[120:123], v116 offset:4096
	s_nop 0
	v_cndmask_b32_e64 v44, v98, v44, s[0:1]
	v_cmp_gt_u32_e64 s[0:1], s76, v124
	s_nop 1
	v_cndmask_b32_e64 v47, v98, v47, s[0:1]
	v_cmp_gt_u32_e64 s[0:1], s76, v125
	ds_read_b128 v[124:127], v117 offset:4096
	s_nop 0
	v_cndmask_b32_e64 v46, v98, v46, s[0:1]
	s_waitcnt lgkmcnt(1)
	s_nop 0
	v_mfma_f32_32x32x16_bf16 v[32:47], v[120:123], v[48:51], v[32:47]
	s_waitcnt lgkmcnt(0)
	v_mfma_f32_32x32x16_bf16 v[32:47], v[124:127], v[52:55], v[32:47]
	ds_read_b128 v[120:123], v118 offset:4096
	ds_read_b128 v[124:127], v118 offset:8192
	s_waitcnt lgkmcnt(1)
	v_mfma_f32_32x32x16_bf16 v[32:47], v[120:123], v[56:59], v[32:47]
	ds_read_b128 v[120:123], v119 offset:4096
	ds_read_b128 v[128:131], v118 offset:12288
	s_waitcnt lgkmcnt(1)
	v_mfma_f32_32x32x16_bf16 v[32:47], v[120:123], v[60:63], v[32:47]
	ds_read_b128 v[120:123], v119 offset:8192
	ds_read_b128 v[132:135], v119 offset:12288
	s_nop 9
	v_exp_f32_e32 v32, v32
	v_exp_f32_e32 v33, v33
	v_exp_f32_e32 v34, v34
	v_exp_f32_e32 v35, v35
	v_exp_f32_e32 v36, v36
	v_exp_f32_e32 v37, v37
	v_exp_f32_e32 v38, v38
	v_exp_f32_e32 v39, v39
	v_add_f32_e32 v136, 0, v32
	v_add_f32_e32 v136, v33, v136
	v_add_f32_e32 v136, v34, v136
	v_add_f32_e32 v136, v35, v136
	v_cvt_pk_bf16_f32 v32, v32, v33
	v_cvt_pk_bf16_f32 v33, v34, v35
	v_cvt_pk_bf16_f32 v34, v36, v37
	v_cvt_pk_bf16_f32 v35, v38, v39
	v_add_f32_e32 v136, v36, v136
	v_add_f32_e32 v136, v37, v136
	v_mfma_f32_32x32x16_bf16 v[16:31], v[124:127], v[32:35], v[16:31]
	v_add_f32_e32 v36, v38, v136
	v_exp_f32_e32 v40, v40
	v_exp_f32_e32 v41, v41
	v_add_f32_e32 v36, v39, v36
	v_exp_f32_e32 v37, v42
	v_exp_f32_e32 v38, v43
	v_exp_f32_e32 v39, v44
	s_waitcnt lgkmcnt(2)
	v_mfma_f32_32x32x16_bf16 v[0:15], v[128:131], v[32:35], v[0:15]
	v_exp_f32_e32 v42, v45
	v_exp_f32_e32 v43, v46
	v_exp_f32_e32 v44, v47
	v_add_f32_e32 v36, v40, v36
	v_cvt_pk_bf16_f32 v32, v40, v41
	v_cvt_pk_bf16_f32 v33, v37, v38
	v_cvt_pk_bf16_f32 v34, v39, v42
	v_cvt_pk_bf16_f32 v35, v43, v44
	v_add_f32_e32 v36, v41, v36
	v_add_f32_e32 v36, v37, v36
	s_waitcnt lgkmcnt(1)
	v_mfma_f32_32x32x16_bf16 v[16:31], v[120:123], v[32:35], v[16:31]
	v_add_f32_e32 v36, v38, v36
	v_add_f32_e32 v36, v39, v36
	v_add_f32_e32 v36, v42, v36
	v_add_f32_e32 v36, v43, v36
	v_add_f32_e32 v36, v44, v36
	v_add_f32_e32 v104, v104, v36
	s_waitcnt lgkmcnt(0)
	v_mfma_f32_32x32x16_bf16 v[0:15], v[132:135], v[32:35], v[0:15]

; template <int TYPE>
; DI void attn_item(const Params& p, int layer, int head, int qt, int dil, int res, int chunk, char* smem) {
;     ...
;     __syncthreads();
;     if (TYPE == 2) {
;       if ((sflag[0] & sflag[1] & sflag[2] & sflag[3] & sflag[4] & sflag[5] & sflag[6] & sflag[7]) != 0) break;
;     }
;     *(uint4*)(sK + swz(kkey0, kchunk)) = kreg0;
;     ...
;     ATT_VSTORE(vreg0, vdc0)
;     __syncthreads();
;     ATT_PREFETCH((kt > kt_lo) ? kt - 1 : kt);
;     ...
;       const int Ks = Kb + 32 * sub;
;       bool need;
;       if (TYPE == 0) need = (Ks <= wq0 + 31) && (Ks + 31 >= wq0 - 128);
;       else if (TYPE == 1) need = (Ks <= wq0 + 31);
;       else need = (Ks < wq0 + 31) && (sflag[wid] == 0);
;       if (!need) continue;
;       const int db = Uq - Ks - 4 * h;
;       f32x16 s1, s2;
;       if (TYPE == 2) {
; #pragma unroll
;         for (int i = 0; i < 16; ++i) { s1[i] = 0.f; s2[i] = 0.f; }
;       } else {
;         const float base = -slope * (float)db - cref;
;         const bool msk = (TYPE == 0) ? true : (__builtin_amdgcn_readfirstlane((Ks + 31 > wq0) ? 1 : 0) != 0);
;         if (msk) {
; #pragma unroll
;           for (int i = 0; i < 16; ++i) {
;             const int ci = (i & 3) + 8 * (i >> 2);
;             const int dist = db - ci;
;             s1[i] = (dist >= 0 && dist <= wlim) ? fmaf(slope, (float)ci, base) : -1e30f;
;             s2[i] = s1[i];
;           }
;         } else {
; #pragma unroll
;           for (int i = 0; i < 16; ++i) {
;             const int ci = (i & 3) + 8 * (i >> 2);
;             s1[i] = fmaf(slope, (float)ci, base);
;             s2[i] = s1[i];
.LBB0_578:
	v_cmp_gt_i32_e32 vcc, v133, v152
	s_barrier
	s_nop 0
	v_subbrev_co_u32_e32 v0, vcc, 0, v133, vcc
	v_lshlrev_b32_e32 v0, 6, v0
	v_add_u32_e32 v66, v0, v137
	v_or_b32_e32 v0, v0, v145
	v_mad_i64_i32 v[66:67], s[4:5], v66, s79, v[154:155]
	s_waitcnt vmcnt(0)
	ds_write_b128 v178, v[118:121]
	ds_write_b16 v179, v114 offset:8192
	ds_write_b16_d16_hi v179, v114 offset:8320
	ds_write_b16 v180, v115 offset:8192
	ds_write_b16_d16_hi v181, v115 offset:8192
	ds_write_b16 v182, v116 offset:8192
	ds_write_b16_d16_hi v183, v116 offset:8192
	ds_write_b16 v184, v117 offset:8192
	ds_write_b16_d16_hi v185, v117 offset:8192
	v_mad_i64_i32 v[68:69], s[4:5], v0, s79, v[156:157]
	global_load_dwordx4 v[118:121], v[66:67], off
	global_load_dwordx4 v[114:117], v[68:69], off
	s_waitcnt lgkmcnt(0)
	s_barrier
	v_cmp_le_i32_e64 s[4:5], v133, v152
	v_add_u32_e32 v0, 32, v139
	v_cmp_le_i32_e32 vcc, v0, v141
	s_and_saveexec_b64 s[68:69], vcc
	s_cbranch_execz .LBB0_584
	v_subrev_u32_e32 v82, 32, v177
	v_add_u32_e32 v66, 63, v139
	v_cvt_f32_i32_e32 v0, v82
	v_cmp_gt_i32_e32 vcc, v66, v174
	s_mov_b64 s[70:71], -1
	v_fma_f32 v0, -v146, v0, -v135
	v_cndmask_b32_e64 v66, 0, 1, vcc
	v_add_f32_e32 v67, v146, v0
	v_readfirstlane_b32 s10, v66
	s_bitcmp1_b32 s10, 0
	s_cselect_b64 s[90:91], -1, 0
	s_and_b64 vcc, exec, s[90:91]
	v_fma_f32 v66, 0, v146, v0
	s_cbranch_vccnz .LBB0_581
	v_pk_fma_f32 v[68:69], v[146:147], s[44:45], v[0:1] op_sel_hi:[1,1,0]
	v_pk_fma_f32 v[70:71], v[146:147], s[46:47], v[0:1] op_sel_hi:[1,1,0]
	v_pk_fma_f32 v[72:73], v[146:147], s[48:49], v[0:1] op_sel_hi:[1,1,0]
	v_pk_fma_f32 v[74:75], v[146:147], s[52:53], v[0:1] op_sel_hi:[1,1,0]
	v_pk_fma_f32 v[76:77], v[146:147], s[54:55], v[0:1] op_sel_hi:[1,1,0]
	v_pk_fma_f32 v[78:79], v[146:147], s[42:43], v[0:1] op_sel_hi:[1,1,0]
	v_pk_fma_f32 v[80:81], v[146:147], s[56:57], v[0:1] op_sel_hi:[1,1,0]
	s_mov_b64 s[70:71], 0

; template <int TYPE>
; DI void attn_item(const Params& p, int layer, int head, int qt, int dil, int res, int chunk, char* smem) {
;     ...
;     __syncthreads();
;     if (TYPE == 2) {
;       if ((sflag[0] & sflag[1] & sflag[2] & sflag[3] & sflag[4] & sflag[5] & sflag[6] & sflag[7]) != 0) break;
;     }
;     *(uint4*)(sK + swz(kkey0, kchunk)) = kreg0;
;     ...
;     ATT_VSTORE(vreg0, vdc0)
;     __syncthreads();
;     ATT_PREFETCH((kt > kt_lo) ? kt - 1 : kt);
;     __builtin_amdgcn_sched_barrier(0);
;     const int Kb = kt * 64;
; #pragma unroll
;     ...
;       const int Ks = Kb + 32 * sub;
;       bool need;
;       if (TYPE == 0) need = (Ks <= wq0 + 31) && (Ks + 31 >= wq0 - 128);
;       else if (TYPE == 1) need = (Ks <= wq0 + 31);
;       else need = (Ks < wq0 + 31) && (sflag[wid] == 0);
;     ...
;       {
;         bf16x8 kf[4];
; #pragma unroll
;         for (int ks = 0; ks < 4; ++ks) kf[ks] = *(const bf16x8*)(sK + swz(32 * sub + ql, 2 * ks + h));
;         if (TYPE == 1) {
;           s1 = mfma32(kf[0], qf[0], s1);
;           s1 = mfma32(kf[1], qf[1], s1);
;           s2 = mfma32(kf[2], qf[2], s2);
;           s2 = mfma32(kf[3], qf[3], s2);
;         } else {
; #pragma unroll
;           for (int ks = 0; ks < 4; ++ks) s1 = mfma32(kf[ks], qf[ks], s1);
;         }
;       }
;       bf16x8 vf[2][2];
; #pragma unroll
;       for (int s = 0; s < 2; ++s)
; #pragma unroll
;         for (int dt = 0; dt < 2; ++dt) vf[s][dt] = *(const bf16x8*)(sV + swz(32 * dt + ql, 4 * sub + 2 * s + h));
;       if (TYPE == 0 || TYPE == 1) {
;         const bool masked = (TYPE == 0) ? true : (Ks + 31 > wq0);
;         bf16x8 pk0, pk1;
;         fx_step(s1, l1, db, masked, wlim, pk0, pk1);
;         O1a = mfma32(vf[0][0], pk0, O1a);
;         O1b = mfma32(vf[0][1], pk0, O1b);
;         O1a = mfma32(vf[1][0], pk1, O1a);
;         O1b = mfma32(vf[1][1], pk1, O1b);
;         if (TYPE == 1) {
;           fx_step(s2, l2, db, masked, wlim, pk0, pk1);
;           O2a = mfma32(vf[0][0], pk0, O2a);
;           O2b = mfma32(vf[0][1], pk0, O2b);
;           O2a = mfma32(vf[1][0], pk1, O2a);
;           O2b = mfma32(vf[1][1], pk1, O2b);
;         }
;       } else {
;         const bool masked = (Ks + 31 >= wq0);
;         float lf[16], lsg[16];
;         float tsum = 0.f;
; #pragma unroll
;         for (int i = 0; i < 16; ++i) {
;           const int ci = (i & 3) + 8 * (i >> 2);
;           const float z = s1[i];
.LBB0_610:
	v_mov_b32_e32 v105, v101
	s_waitcnt lgkmcnt(0)
	s_barrier
	ds_read_b32 v0, v100
	ds_read_b32 v34, v104
	v_mov_b32_e32 v107, v101
	v_mov_b32_e32 v109, v101
	ds_read_b32 v35, v106
	ds_read_b32 v36, v108
	v_mov_b32_e32 v111, v101
	v_mov_b32_e32 v113, v101
	ds_read_b32 v37, v110
	ds_read_b32 v38, v112
	v_mov_b32_e32 v115, v101
	v_mov_b32_e32 v117, v101
	ds_read_b32 v39, v114
	ds_read_b32 v40, v116
	s_waitcnt vmcnt(0)
	s_or_b64 s[48:49], s[48:49], exec
	s_waitcnt lgkmcnt(0)
	v_and_b32_e32 v0, v34, v0
	v_bitop3_b32 v0, v0, v36, v35 bitop3:0x80
	v_bitop3_b32 v0, v0, v38, v37 bitop3:0x80
	v_bitop3_b32 v0, v0, v40, v39 bitop3:0x80
	v_cmp_eq_u32_e64 s[0:1], 0, v0
	s_and_saveexec_b64 s[52:53], s[0:1]
	s_cbranch_execz .LBB0_609
	v_min_u32_e32 v0, 1, v132
	v_lshlrev_b32_e32 v0, 6, v0
	v_add_u32_e32 v34, v137, v99
	v_sub_u32_e32 v34, v34, v0
	v_add_u32_e32 v35, v136, v99
	v_sub_u32_e32 v0, v35, v0
	v_mad_i64_i32 v[34:35], s[0:1], v34, s60, v[120:121]
	ds_write_b128 v139, v[74:77]
	ds_write_b16 v140, v70 offset:8192
	ds_write_b16_d16_hi v140, v70 offset:8320
	ds_write_b16 v141, v71 offset:8192
	ds_write_b16_d16_hi v142, v71 offset:8192
	ds_write_b16 v143, v72 offset:8192
	ds_write_b16_d16_hi v144, v72 offset:8192
	ds_write_b16 v145, v73 offset:8192
	ds_write_b16_d16_hi v146, v73 offset:8192
	v_mad_u64_u32 v[36:37], s[0:1], v0, s60, v[122:123]
	global_load_dwordx4 v[74:77], v[34:35], off
	global_load_dwordx4 v[70:73], v[36:37], off
	s_waitcnt lgkmcnt(0)
	s_barrier
	v_add_u32_e32 v0, 0x3fe0, v99
	v_cmp_lt_i32_e64 s[0:1], v0, v133
	s_and_saveexec_b64 s[54:55], s[0:1]
	s_cbranch_execz .LBB0_615
	ds_read_b32 v0, v124
	s_waitcnt lgkmcnt(0)
	v_cmp_eq_u32_e64 s[0:1], 0, v0
	s_and_saveexec_b64 s[56:57], s[0:1]
	s_cbranch_execz .LBB0_614
	ds_read_b128 v[34:37], v147 offset:4096
	ds_read_b128 v[82:85], v148 offset:4096
	v_add_u32_e32 v0, 0x3fff, v99
	v_add_u32_e32 v105, 27, v135
	v_add_u32_e32 v107, 26, v135
	s_waitcnt lgkmcnt(1)
	v_mfma_f32_32x32x16_bf16 v[34:49], v[34:37], v[50:53], 0
	v_cmp_lt_i32_e64 s[2:3], v0, v130
	v_cmp_lt_i32_e64 s[0:1], 0, v105
	v_cmp_lt_i32_e64 s[4:5], 0, v107
	v_add_u32_e32 v109, 25, v135
	v_cmp_lt_i32_e64 s[6:7], 0, v109
	s_or_b64 s[0:1], s[2:3], s[0:1]
	s_waitcnt lgkmcnt(0)
	v_mfma_f32_32x32x16_bf16 v[34:49], v[82:85], v[54:57], v[34:49]
	ds_read_b128 v[152:155], v149 offset:4096
	ds_read_b128 v[94:97], v149 offset:8192
	ds_read_b128 v[166:169], v150 offset:4096
	ds_read_b128 v[90:93], v149 offset:12288
	ds_read_b128 v[86:89], v150 offset:8192
	ds_read_b128 v[82:85], v150 offset:12288
	s_waitcnt lgkmcnt(5)
	v_mfma_f32_32x32x16_bf16 v[34:49], v[152:155], v[58:61], v[34:49]
	s_waitcnt lgkmcnt(3)
	v_mfma_f32_32x32x16_bf16 v[34:49], v[166:169], v[62:65], v[34:49]
	s_nop 11
	v_exp_f32_e64 v0, -|v34|
	v_exp_f32_e64 v105, -|v35|
	v_exp_f32_e64 v107, -|v36|
	v_max_f32_e32 v34, v34, v34
	v_add_f32_e32 v0, 1.0, v0
	v_add_f32_e32 v105, 1.0, v105
	v_log_f32_e32 v0, v0
	v_add_f32_e32 v107, 1.0, v107
	v_log_f32_e32 v105, v105
	v_log_f32_e32 v107, v107
	v_exp_f32_e64 v109, -|v37|
	v_max_f32_e32 v35, v35, v35
	v_max_f32_e32 v36, v36, v36
	v_max_f32_e32 v111, 0, v34
	v_min_f32_e32 v34, 0, v34
	v_max_f32_e32 v113, 0, v35
	v_min_f32_e32 v35, 0, v35
	v_max_f32_e32 v115, 0, v36
	v_min_f32_e32 v36, 0, v36
	v_add_f32_e32 v111, v111, v0
	v_sub_f32_e32 v0, v34, v0
	v_add_f32_e32 v34, v113, v105
	v_sub_f32_e32 v35, v35, v105
	v_add_f32_e32 v105, v115, v107
	v_sub_f32_e32 v36, v36, v107
	v_cndmask_b32_e64 v107, 0, -v111, s[0:1]
	v_cndmask_b32_e64 v0, v128, v0, s[0:1]
	s_or_b64 s[0:1], s[2:3], s[4:5]
	v_cndmask_b32_e64 v113, v128, v35, s[0:1]
	v_add_f32_e32 v35, 1.0, v109
	v_log_f32_e32 v35, v35
	v_cndmask_b32_e64 v111, 0, -v34, s[0:1]
	s_or_b64 s[0:1], s[2:3], s[6:7]
	v_cndmask_b32_e64 v115, v128, v36, s[0:1]
	v_max_f32_e32 v36, v37, v37
	v_max_f32_e32 v37, 0, v36
	v_min_f32_e32 v36, 0, v36
	v_add_f32_e32 v37, v37, v35
	v_sub_f32_e32 v35, v36, v35
	v_add_u32_e32 v36, 24, v135
	v_cndmask_b32_e64 v105, 0, -v105, s[0:1]
	v_cmp_lt_i32_e64 s[0:1], 0, v36
	v_exp_f32_e64 v36, -|v38|
	s_or_b64 s[0:1], s[2:3], s[0:1]
	v_cndmask_b32_e64 v109, v128, v35, s[0:1]
	v_cndmask_b32_e64 v37, 0, -v37, s[0:1]
	v_add_f32_e32 v35, 1.0, v36
	v_log_f32_e32 v35, v35
	v_max_f32_e32 v36, v38, v38
	v_max_f32_e32 v38, 0, v36
	v_min_f32_e32 v36, 0, v36
	v_add_f32_e32 v38, v38, v35
	v_sub_f32_e32 v35, v36, v35
	v_add_u32_e32 v36, 19, v135
	v_cmp_lt_i32_e64 s[0:1], 0, v36
	v_exp_f32_e64 v36, -|v39|
	s_or_b64 s[0:1], s[2:3], s[0:1]
	v_cndmask_b32_e64 v117, v128, v35, s[0:1]
	v_cndmask_b32_e64 v38, 0, -v38, s[0:1]
	v_add_f32_e32 v35, 1.0, v36
	v_log_f32_e32 v35, v35
	v_max_f32_e32 v36, v39, v39
	v_max_f32_e32 v39, 0, v36
	v_min_f32_e32 v36, 0, v36
	v_add_f32_e32 v39, v39, v35
	v_sub_f32_e32 v35, v36, v35
	v_add_u32_e32 v36, 18, v135
	v_cmp_lt_i32_e64 s[0:1], 0, v36
	v_exp_f32_e64 v36, -|v40|
	s_or_b64 s[0:1], s[2:3], s[0:1]
	v_cndmask_b32_e64 v151, v128, v35, s[0:1]
	v_cndmask_b32_e64 v39, 0, -v39, s[0:1]
	v_add_f32_e32 v35, 1.0, v36
	v_log_f32_e32 v35, v35
	v_max_f32_e32 v36, v40, v40
	v_max_f32_e32 v40, 0, v36
	v_min_f32_e32 v36, 0, v36
	v_add_f32_e32 v40, v40, v35
	v_sub_f32_e32 v35, v36, v35
	v_add_u32_e32 v36, 17, v135
	v_cmp_lt_i32_e64 s[0:1], 0, v36
	v_exp_f32_e64 v36, -|v41|
	s_or_b64 s[0:1], s[2:3], s[0:1]
	v_cndmask_b32_e64 v156, v128, v35, s[0:1]
	v_cndmask_b32_e64 v40, 0, -v40, s[0:1]
	v_add_f32_e32 v35, 1.0, v36
	v_log_f32_e32 v35, v35
	v_max_f32_e32 v36, v41, v41
	v_max_f32_e32 v41, 0, v36
	v_min_f32_e32 v36, 0, v36
	v_add_f32_e32 v41, v41, v35
	v_sub_f32_e32 v35, v36, v35
	v_add_u32_e32 v36, 16, v135
	v_cmp_lt_i32_e64 s[0:1], 0, v36
	v_exp_f32_e64 v36, -|v42|
; DI float bflo(unsigned u) { return __uint_as_float(u << 16); }
; DI float bfhi(unsigned u) { return __uint_as_float(u & 0xffff0000u); }
; DI f32x16 mfma32(bf16x8 a, bf16x8 b, f32x16 c) { return __builtin_amdgcn_mfma_f32_32x32x16_bf16(a, b, c, 0, 0, 0); }
; DI float ex2(float x) { return __builtin_amdgcn_exp2f(x); }
; DI float lg2(float x) { return __builtin_amdgcn_logf(x); }
; template <int TYPE>
; DI void attn_item(const Params& p, int layer, int head, int qt, int dil, int res, int chunk, char* smem) {
;     ...
;         float lf[16], lsg[16];
;         float tsum = 0.f;
; #pragma unroll
;         for (int i = 0; i < 16; ++i) {
;           const int ci = (i & 3) + 8 * (i >> 2);
;           const float z = s1[i];
;           const float t = lg2(1.f + ex2(-fabsf(z)));
;           float f = -(fmaxf(z, 0.f) + t);
;           float g = fminf(z, 0.f) - t;
;           if (masked) {
;             const bool ok = (db - ci) > 0;
;             f = ok ? f : 0.f;
;             g = ok ? g : -1e30f;
;           }
;           lf[i] = f;
;           lsg[i] = g;
;           tsum += f;
;         }
;         unsigned hi[8], lo[8];
; #pragma unroll
;         for (int i = 0; i < 8; ++i) {
;           hi[i] = pack2(lf[2 * i], lf[2 * i + 1]);
;           lo[i] = pack2(lf[2 * i] - bflo(hi[i]), lf[2 * i + 1] - bfhi(hi[i]));
;         }
;         f32x16 aft;
; #pragma unroll
;         for (int i = 0; i < 16; ++i) aft[i] = 0.f;
;         aft = mfma32(Tm0, mk8(hi[0], hi[1], hi[2], hi[3]), aft);
;         aft = mfma32(Tm1, mk8(hi[4], hi[5], hi[6], hi[7]), aft);
;         aft = mfma32(Tm0, mk8(lo[0], lo[1], lo[2], lo[3]), aft);
;         aft = mfma32(Tm1, mk8(lo[4], lo[5], lo[6], lo[7]), aft);
	s_or_b64 s[0:1], s[2:3], s[0:1]
	v_cndmask_b32_e64 v157, v128, v35, s[0:1]
	v_cndmask_b32_e64 v41, 0, -v41, s[0:1]
	v_add_f32_e32 v35, 1.0, v36
	v_log_f32_e32 v35, v35
	v_max_f32_e32 v36, v42, v42
	v_max_f32_e32 v42, 0, v36
	v_min_f32_e32 v36, 0, v36
	v_add_f32_e32 v42, v42, v35
	v_sub_f32_e32 v35, v36, v35
	v_add_u32_e32 v36, 11, v135
	v_cmp_lt_i32_e64 s[0:1], 0, v36
	v_exp_f32_e64 v36, -|v43|
	s_or_b64 s[0:1], s[2:3], s[0:1]
	v_cndmask_b32_e64 v165, v128, v35, s[0:1]
	v_cndmask_b32_e64 v42, 0, -v42, s[0:1]
	v_add_f32_e32 v35, 1.0, v36
	v_log_f32_e32 v35, v35
	v_max_f32_e32 v36, v43, v43
	v_max_f32_e32 v43, 0, v36
	v_min_f32_e32 v36, 0, v36
	v_add_f32_e32 v43, v43, v35
	v_sub_f32_e32 v35, v36, v35
	v_add_u32_e32 v36, 10, v135
	v_cmp_lt_i32_e64 s[0:1], 0, v36
	v_exp_f32_e64 v36, -|v44|
	s_or_b64 s[0:1], s[2:3], s[0:1]
	v_cndmask_b32_e64 v174, v128, v35, s[0:1]
	v_cndmask_b32_e64 v167, 0, -v43, s[0:1]
	v_add_f32_e32 v35, 1.0, v36
	v_log_f32_e32 v35, v35
	v_max_f32_e32 v36, v44, v44
	v_max_f32_e32 v43, 0, v36
	v_min_f32_e32 v36, 0, v36
	v_add_f32_e32 v43, v43, v35
	v_sub_f32_e32 v35, v36, v35
	v_add_u32_e32 v36, 9, v135
	v_cmp_lt_i32_e64 s[0:1], 0, v36
	v_exp_f32_e64 v36, -|v45|
	s_or_b64 s[0:1], s[2:3], s[0:1]
	v_cndmask_b32_e64 v175, v128, v35, s[0:1]
	v_cndmask_b32_e64 v171, 0, -v43, s[0:1]
	v_add_f32_e32 v35, 1.0, v36
	v_log_f32_e32 v35, v35
	v_max_f32_e32 v36, v45, v45
	v_max_f32_e32 v43, 0, v36
	v_min_f32_e32 v36, 0, v36
	v_add_f32_e32 v43, v43, v35
	v_sub_f32_e32 v35, v36, v35
	v_add_u32_e32 v36, 8, v135
	v_cmp_lt_i32_e64 s[0:1], 0, v36
	v_exp_f32_e64 v36, -|v46|
	s_or_b64 s[0:1], s[2:3], s[0:1]
	v_cndmask_b32_e64 v176, v128, v35, s[0:1]
	v_cndmask_b32_e64 v172, 0, -v43, s[0:1]
	v_add_f32_e32 v35, 1.0, v36
	v_log_f32_e32 v35, v35
	v_max_f32_e32 v36, v46, v46
	v_max_f32_e32 v43, 0, v36
	v_min_f32_e32 v36, 0, v36
	v_add_f32_e32 v43, v43, v35
	v_sub_f32_e32 v35, v36, v35
	v_add_u32_e32 v36, 3, v135
	v_cmp_lt_i32_e64 s[0:1], 0, v36
	v_exp_f32_e64 v36, -|v47|
	s_or_b64 s[0:1], s[2:3], s[0:1]
	v_cndmask_b32_e64 v177, v128, v35, s[0:1]
	v_cndmask_b32_e64 v173, 0, -v43, s[0:1]
	v_add_f32_e32 v35, 1.0, v36
	v_log_f32_e32 v35, v35
	v_max_f32_e32 v36, v47, v47
	v_max_f32_e32 v43, 0, v36
	v_min_f32_e32 v36, 0, v36
	v_add_f32_e32 v43, v43, v35
	v_sub_f32_e32 v35, v36, v35
	v_add_u32_e32 v36, 2, v135
	v_cmp_lt_i32_e64 s[0:1], 0, v36
	v_exp_f32_e64 v36, -|v48|
	s_or_b64 s[0:1], s[2:3], s[0:1]
	v_cndmask_b32_e64 v179, v128, v35, s[0:1]
	v_add_f32_e32 v34, 0, v107
	v_add_f32_e32 v35, 1.0, v36
	v_log_f32_e32 v35, v35
	v_add_f32_e32 v34, v111, v34
	v_max_f32_e32 v36, v48, v48
	v_add_f32_e32 v34, v105, v34
	v_cndmask_b32_e64 v178, 0, -v43, s[0:1]
	v_max_f32_e32 v43, 0, v36
	v_min_f32_e32 v36, 0, v36
	v_add_f32_e32 v34, v37, v34
	v_add_f32_e32 v43, v43, v35
	v_sub_f32_e32 v35, v36, v35
	v_add_u32_e32 v36, 1, v135
	v_add_f32_e32 v34, v38, v34
	v_cmp_lt_i32_e64 s[0:1], 0, v36
	v_exp_f32_e64 v36, -|v49|
	v_add_f32_e32 v34, v39, v34
	v_add_f32_e32 v34, v40, v34
	v_add_f32_e32 v34, v41, v34
	s_or_b64 s[0:1], s[2:3], s[0:1]
	v_add_f32_e32 v34, v42, v34
	v_cndmask_b32_e64 v181, v128, v35, s[0:1]
	v_add_f32_e32 v35, 1.0, v36
	v_add_f32_e32 v34, v167, v34
	v_log_f32_e32 v35, v35
	v_add_f32_e32 v34, v171, v34
	v_add_f32_e32 v34, v172, v34
	v_max_f32_e32 v36, v49, v49
	v_add_f32_e32 v34, v173, v34
	v_cndmask_b32_e64 v180, 0, -v43, s[0:1]
	v_max_f32_e32 v43, 0, v36
	v_cmp_lt_i32_e64 s[0:1], 0, v135
	v_add_f32_e32 v34, v178, v34
	v_add_f32_e32 v43, v43, v35
	s_or_b64 s[0:1], s[2:3], s[0:1]
	v_add_f32_e32 v34, v180, v34
	v_min_f32_e32 v36, 0, v36
	v_cndmask_b32_e64 v182, 0, -v43, s[0:1]
	v_sub_f32_e32 v35, v36, v35
	v_add_f32_e32 v184, v182, v34
	v_cvt_pk_bf16_f32 v34, v107, v111
	v_cndmask_b32_e64 v183, v128, v35, s[0:1]
	v_lshlrev_b32_e32 v35, 16, v34
	v_and_b32_e32 v36, 0xffff0000, v34
	v_sub_f32_e32 v35, v107, v35
	v_sub_f32_e32 v36, v111, v36
	v_cvt_pk_bf16_f32 v152, v35, v36
	v_cvt_pk_bf16_f32 v35, v105, v37
	v_lshlrev_b32_e32 v36, 16, v35
	v_and_b32_e32 v43, 0xffff0000, v35
	v_sub_f32_e32 v36, v105, v36
	v_sub_f32_e32 v37, v37, v43
	v_cvt_pk_bf16_f32 v153, v36, v37
	v_cvt_pk_bf16_f32 v36, v38, v39
	v_lshlrev_b32_e32 v37, 16, v36
	v_sub_f32_e32 v37, v38, v37
	v_and_b32_e32 v38, 0xffff0000, v36
	v_sub_f32_e32 v38, v39, v38
	v_cvt_pk_bf16_f32 v154, v37, v38
	v_cvt_pk_bf16_f32 v37, v40, v41
	v_lshlrev_b32_e32 v38, 16, v37
	v_and_b32_e32 v39, 0xffff0000, v37
	v_sub_f32_e32 v38, v40, v38
	v_sub_f32_e32 v39, v41, v39
	v_cvt_pk_bf16_f32 v166, v42, v167
	v_cvt_pk_bf16_f32 v155, v38, v39
	v_lshlrev_b32_e32 v38, 16, v166
	v_sub_f32_e32 v105, v42, v38
	v_mfma_f32_32x32x16_bf16 v[34:49], v[66:69], v[34:37], 0
	v_and_b32_e32 v107, 0xffff0000, v166
	v_sub_f32_e32 v107, v167, v107
	v_cvt_pk_bf16_f32 v167, v171, v172
	v_cvt_pk_bf16_f32 v168, v173, v178
	v_cvt_pk_bf16_f32 v169, v180, v182
	v_cvt_pk_bf16_f32 v170, v105, v107
	v_lshlrev_b32_e32 v105, 16, v167
	v_mfma_f32_32x32x16_bf16 v[34:49], v[78:81], v[166:169], v[34:49]
	v_and_b32_e32 v107, 0xffff0000, v167
	v_sub_f32_e32 v105, v171, v105
	v_sub_f32_e32 v107, v172, v107
	v_cvt_pk_bf16_f32 v171, v105, v107
	v_lshlrev_b32_e32 v105, 16, v168
	v_and_b32_e32 v107, 0xffff0000, v168
	v_sub_f32_e32 v105, v173, v105
	v_mfma_f32_32x32x16_bf16 v[34:49], v[66:69], v[152:155], v[34:49]
	v_sub_f32_e32 v107, v178, v107
	v_cvt_pk_bf16_f32 v172, v105, v107
	v_lshlrev_b32_e32 v105, 16, v169
	v_and_b32_e32 v107, 0xffff0000, v169
	v_sub_f32_e32 v105, v180, v105
	v_sub_f32_e32 v107, v182, v107
	v_cvt_pk_bf16_f32 v173, v105, v107
	s_nop 1
	v_mfma_f32_32x32x16_bf16 v[34:49], v[78:81], v[170:173], v[34:49]
	s_nop 11
	v_add_f32_e32 v0, v0, v34
	v_add_f32_e32 v34, v113, v35
	v_add_f32_e32 v35, v115, v36
	v_add_f32_e32 v36, v109, v37
	v_add_f32_e32 v37, v117, v38
	v_add_f32_e32 v38, v151, v39
	v_add_f32_e32 v39, v156, v40
	v_add_f32_e32 v40, v157, v41
	v_add_f32_e32 v0, v138, v0
	v_add_f32_e32 v34, v138, v34
	v_add_f32_e32 v35, v138, v35
	v_add_f32_e32 v36, v138, v36
	v_add_f32_e32 v37, v138, v37
	v_add_f32_e32 v38, v138, v38
	v_add_f32_e32 v39, v138, v39
	v_add_f32_e32 v40, v138, v40
	v_exp_f32_e32 v0, v0
	v_exp_f32_e32 v34, v34
	v_exp_f32_e32 v35, v35
	v_exp_f32_e32 v36, v36
	v_exp_f32_e32 v37, v37
	v_exp_f32_e32 v38, v38
	v_exp_f32_e32 v39, v39
	v_exp_f32_e32 v40, v40
	v_cvt_pk_bf16_f32 v34, v0, v34
	v_cvt_pk_bf16_f32 v35, v35, v36
	v_cvt_pk_bf16_f32 v36, v37, v38
	v_cvt_pk_bf16_f32 v37, v39, v40
	v_add_f32_e32 v41, v165, v42
	v_add_f32_e32 v42, v174, v43
	v_mfma_f32_32x32x16_bf16 v[18:33], v[94:97], v[34:37], v[18:33]
	v_add_f32_e32 v43, v175, v44
	v_add_f32_e32 v44, v176, v45
	v_add_f32_e32 v45, v177, v46
	v_add_f32_e32 v38, v179, v47
	v_add_f32_e32 v39, v181, v48
	v_add_f32_e32 v41, v138, v41
	v_add_f32_e32 v42, v138, v42
	s_waitcnt lgkmcnt(2)
; DI f32x16 mfma32(bf16x8 a, bf16x8 b, f32x16 c) { return __builtin_amdgcn_mfma_f32_32x32x16_bf16(a, b, c, 0, 0, 0); }
; DI float ex2(float x) { return __builtin_amdgcn_exp2f(x); }
; template <int TYPE>
; DI void attn_item(const Params& p, int layer, int head, int qt, int dil, int res, int chunk, char* smem) {
;     ...
;         float w[16];
; #pragma unroll
;         for (int i = 0; i < 16; ++i) w[i] = ex2(lsg[i] + aft[i] + carry);
;         tsum += __shfl_xor(tsum, 32);
;         carry += tsum;
;         bf16x8 pk0 = mk8(pack2(w[0], w[1]), pack2(w[2], w[3]), pack2(w[4], w[5]), pack2(w[6], w[7]));
;         bf16x8 pk1 = mk8(pack2(w[8], w[9]), pack2(w[10], w[11]), pack2(w[12], w[13]), pack2(w[14], w[15]));
;         O1a = mfma32(vf[0][0], pk0, O1a);
;         O1b = mfma32(vf[0][1], pk0, O1b);
;         O1a = mfma32(vf[1][0], pk1, O1a);
;         O1b = mfma32(vf[1][1], pk1, O1b);
	v_mfma_f32_32x32x16_bf16 v[2:17], v[90:93], v[34:37], v[2:17]
	v_add_f32_e32 v34, v183, v49
	v_add_f32_e32 v43, v138, v43
	v_add_f32_e32 v44, v138, v44
	v_add_f32_e32 v45, v138, v45
	v_add_f32_e32 v38, v138, v38
	v_add_f32_e32 v39, v138, v39
	v_add_f32_e32 v34, v138, v34
	v_exp_f32_e32 v41, v41
	v_exp_f32_e32 v42, v42
	v_exp_f32_e32 v43, v43
	v_exp_f32_e32 v44, v44
	v_exp_f32_e32 v0, v45
	v_exp_f32_e32 v38, v38
	v_exp_f32_e32 v39, v39
	v_exp_f32_e32 v37, v34
	v_cvt_pk_bf16_f32 v34, v41, v42
	v_cvt_pk_bf16_f32 v35, v43, v44
	v_cvt_pk_bf16_f32 v36, v0, v38
	v_cvt_pk_bf16_f32 v37, v39, v37
	ds_bpermute_b32 v0, v159, v184
	s_waitcnt lgkmcnt(0)
	v_add_f32_e32 v0, v184, v0
	v_mfma_f32_32x32x16_bf16 v[18:33], v[86:89], v[34:37], v[18:33]
	v_add_f32_e32 v138, v138, v0
	v_mfma_f32_32x32x16_bf16 v[2:17], v[82:85], v[34:37], v[2:17]

; DI f32x16 mfma32(bf16x8 a, bf16x8 b, f32x16 c) { return __builtin_amdgcn_mfma_f32_32x32x16_bf16(a, b, c, 0, 0, 0); }
; template <int TYPE>
; DI void attn_item(const Params& p, int layer, int head, int qt, int dil, int res, int chunk, char* smem) {
;     ...
;     __syncthreads();
;     if (TYPE == 2) {
;       if ((sflag[0] & sflag[1] & sflag[2] & sflag[3] & sflag[4] & sflag[5] & sflag[6] & sflag[7]) != 0) break;
;     }
;     *(uint4*)(sK + swz(kkey0, kchunk)) = kreg0;
;     ...
;     ATT_VSTORE(vreg0, vdc0)
;     __syncthreads();
;     ATT_PREFETCH((kt > kt_lo) ? kt - 1 : kt);
;     ...
;         const float base = -slope * (float)db - cref;
;         const bool msk = (TYPE == 0) ? true : (__builtin_amdgcn_readfirstlane((Ks + 31 > wq0) ? 1 : 0) != 0);
;         if (msk) {
; #pragma unroll
;           for (int i = 0; i < 16; ++i) {
;             const int ci = (i & 3) + 8 * (i >> 2);
;             const int dist = db - ci;
;             s1[i] = (dist >= 0 && dist <= wlim) ? fmaf(slope, (float)ci, base) : -1e30f;
;             s2[i] = s1[i];
;           }
;         } else {
; #pragma unroll
;           for (int i = 0; i < 16; ++i) {
;             const int ci = (i & 3) + 8 * (i >> 2);
;             s1[i] = fmaf(slope, (float)ci, base);
;             s2[i] = s1[i];
;           }
;         }
;       }
;       {
;         bf16x8 kf[4];
; #pragma unroll
;         for (int ks = 0; ks < 4; ++ks) kf[ks] = *(const bf16x8*)(sK + swz(32 * sub + ql, 2 * ks + h));
;         if (TYPE == 1) {
;           s1 = mfma32(kf[0], qf[0], s1);
;           s1 = mfma32(kf[1], qf[1], s1);
;           s2 = mfma32(kf[2], qf[2], s2);
;           s2 = mfma32(kf[3], qf[3], s2);
;         } else {
; #pragma unroll
;           for (int ks = 0; ks < 4; ++ks) s1 = mfma32(kf[ks], qf[ks], s1);
;         }
;       }
;       bf16x8 vf[2][2];
; #pragma unroll
;       for (int s = 0; s < 2; ++s)
; #pragma unroll
;         for (int dt = 0; dt < 2; ++dt) vf[s][dt] = *(const bf16x8*)(sV + swz(32 * dt + ql, 4 * sub + 2 * s + h));
;       if (TYPE == 0 || TYPE == 1) {
;         const bool masked = (TYPE == 0) ? true : (Ks + 31 > wq0);
;         bf16x8 pk0, pk1;
;         fx_step(s1, l1, db, masked, wlim, pk0, pk1);
;         O1a = mfma32(vf[0][0], pk0, O1a);
;         O1b = mfma32(vf[0][1], pk0, O1b);
;         O1a = mfma32(vf[1][0], pk1, O1a);
;         O1b = mfma32(vf[1][1], pk1, O1b);
.LBB0_632:
	v_cmp_gt_i32_e32 vcc, v81, v99
	s_barrier
	s_nop 0
	v_subbrev_co_u32_e32 v32, vcc, 0, v81, vcc
	v_lshlrev_b32_e32 v34, 6, v32
	v_add_u32_e32 v32, v34, v100
	v_ashrrev_i32_e32 v33, 31, v32
	v_or_b32_e32 v34, v34, v75
	v_lshlrev_b64 v[32:33], v79, v[32:33]
	v_ashrrev_i32_e32 v35, 31, v34
	v_lshl_add_u64 v[32:33], v[32:33], 0, v[86:87]
	v_lshlrev_b64 v[34:35], v79, v[34:35]
	v_lshl_add_u64 v[34:35], v[34:35], 0, v[86:87]
	v_mad_u64_u32 v[36:37], s[0:1], v32, s62, v[88:89]
	v_mad_i32_i24 v37, v33, s62, v37
	v_mad_u64_u32 v[32:33], s[0:1], v34, s62, v[90:91]
	s_waitcnt vmcnt(0)
	ds_write_b128 v107, v[68:71]
	ds_write_b16 v108, v64 offset:8192
	ds_write_b16_d16_hi v108, v64 offset:8320
	ds_write_b16 v109, v65 offset:8192
	ds_write_b16_d16_hi v110, v65 offset:8192
	ds_write_b16 v111, v66 offset:8192
	ds_write_b16_d16_hi v112, v66 offset:8192
	ds_write_b16 v113, v67 offset:8192
	ds_write_b16_d16_hi v114, v67 offset:8192
	v_mad_i32_i24 v33, v35, s62, v33
	global_load_dwordx4 v[68:71], v[36:37], off
	global_load_dwordx4 v[64:67], v[32:33], off
	s_waitcnt lgkmcnt(0)
	s_barrier
	v_cmp_le_i32_e32 vcc, v81, v99
	v_add_u32_e32 v32, 1, v106
	v_cmp_le_i32_e64 s[0:1], v32, v101
	v_add_u32_e32 v32, 32, v106
	v_cmp_ge_i32_e64 s[2:3], v32, v102
	s_and_b64 s[0:1], s[0:1], s[2:3]
	s_and_saveexec_b64 s[2:3], s[0:1]
	s_cbranch_execz .LBB0_634
	v_add_u32_e32 v32, 1, v105
	v_cvt_f32_i32_e32 v33, v32
	v_cmp_gt_u32_e64 s[0:1], s67, v32
	v_add_u32_e32 v36, -2, v105
	v_add_u32_e32 v37, -1, v105
	v_fma_f32 v46, -v92, v33, -v104
	v_fma_f32 v33, 0, v92, v46
	v_add_f32_e32 v34, v92, v46
	v_cndmask_b32_e64 v32, v98, v33, s[0:1]
	v_cmp_gt_u32_e64 s[0:1], s67, v105
	v_add_u32_e32 v38, -8, v105
	v_add_u32_e32 v39, -7, v105
	v_cndmask_b32_e64 v33, v98, v34, s[0:1]
	v_pk_fma_f32 v[34:35], v[92:93], s[18:19], v[46:47] op_sel_hi:[1,1,0]
	v_cmp_gt_u32_e64 s[0:1], s67, v36
	v_add_u32_e32 v40, -10, v105
	v_add_u32_e32 v41, -9, v105
	v_cndmask_b32_e64 v35, v98, v35, s[0:1]
	v_cmp_gt_u32_e64 s[0:1], s67, v37
	v_pk_fma_f32 v[36:37], v[92:93], s[36:37], v[46:47] op_sel_hi:[1,1,0]
	v_add_u32_e32 v42, -16, v105
	v_cndmask_b32_e64 v34, v98, v34, s[0:1]
	v_cmp_gt_u32_e64 s[0:1], s67, v38
	v_add_u32_e32 v43, -15, v105
	ds_read_b128 v[120:123], v115 offset:4096
	v_cndmask_b32_e64 v37, v98, v37, s[0:1]
	v_cmp_gt_u32_e64 s[0:1], s67, v39
	v_pk_fma_f32 v[38:39], v[92:93], s[40:41], v[46:47] op_sel_hi:[1,1,0]
	v_subrev_u32_e32 v44, 18, v105
	v_cndmask_b32_e64 v36, v98, v36, s[0:1]
	v_cmp_gt_u32_e64 s[0:1], s67, v40
	v_subrev_u32_e32 v45, 17, v105
	v_subrev_u32_e32 v119, 23, v105
	v_cndmask_b32_e64 v39, v98, v39, s[0:1]
	v_cmp_gt_u32_e64 s[0:1], s67, v41
	v_pk_fma_f32 v[40:41], v[92:93], s[42:43], v[46:47] op_sel_hi:[1,1,0]
	v_subrev_u32_e32 v124, 25, v105
	v_cndmask_b32_e64 v38, v98, v38, s[0:1]
	v_cmp_gt_u32_e64 s[0:1], s67, v42
	s_nop 1
	v_cndmask_b32_e64 v41, v98, v41, s[0:1]
	v_cmp_gt_u32_e64 s[0:1], s67, v43
	v_pk_fma_f32 v[42:43], v[92:93], s[44:45], v[46:47] op_sel_hi:[1,1,0]
	v_subrev_u32_e32 v47, 24, v105
	v_cndmask_b32_e64 v40, v98, v40, s[0:1]
	v_cmp_gt_u32_e64 s[0:1], s67, v44
	s_nop 1
	v_cndmask_b32_e64 v43, v98, v43, s[0:1]
	v_cmp_gt_u32_e64 s[0:1], s67, v45
	v_pk_fma_f32 v[44:45], v[92:93], s[46:47], v[46:47] op_sel_hi:[1,1,0]
	s_nop 0
	v_cndmask_b32_e64 v42, v98, v42, s[0:1]
	v_cmp_gt_u32_e64 s[0:1], s67, v47
	v_pk_fma_f32 v[46:47], v[92:93], s[48:49], v[46:47] op_sel_hi:[1,1,0]
	s_nop 0
	v_cndmask_b32_e64 v45, v98, v45, s[0:1]
	v_cmp_gt_u32_e64 s[0:1], s67, v119
	v_subrev_u32_e32 v119, 26, v105
	s_nop 0
	v_cndmask_b32_e64 v44, v98, v44, s[0:1]
	v_cmp_gt_u32_e64 s[0:1], s67, v119
	s_nop 1
	v_cndmask_b32_e64 v47, v98, v47, s[0:1]
	v_cmp_gt_u32_e64 s[0:1], s67, v124
	ds_read_b128 v[124:127], v116 offset:4096
	s_nop 0
	v_cndmask_b32_e64 v46, v98, v46, s[0:1]
	s_waitcnt lgkmcnt(1)
	s_nop 0
	v_mfma_f32_32x32x16_bf16 v[32:47], v[120:123], v[48:51], v[32:47]
	s_waitcnt lgkmcnt(0)
	v_mfma_f32_32x32x16_bf16 v[32:47], v[124:127], v[52:55], v[32:47]
	ds_read_b128 v[120:123], v117 offset:4096
	ds_read_b128 v[124:127], v117 offset:8192
	s_waitcnt lgkmcnt(1)
	v_mfma_f32_32x32x16_bf16 v[32:47], v[120:123], v[56:59], v[32:47]
	ds_read_b128 v[120:123], v118 offset:4096
	ds_read_b128 v[128:131], v117 offset:12288
	s_waitcnt lgkmcnt(1)
	v_mfma_f32_32x32x16_bf16 v[32:47], v[120:123], v[60:63], v[32:47]
	ds_read_b128 v[120:123], v118 offset:8192
	ds_read_b128 v[132:135], v118 offset:12288
	s_nop 9
	v_exp_f32_e32 v32, v32
	v_exp_f32_e32 v33, v33
	v_exp_f32_e32 v34, v34
	v_exp_f32_e32 v35, v35
	v_exp_f32_e32 v36, v36
	v_exp_f32_e32 v37, v37
	v_exp_f32_e32 v38, v38
	v_exp_f32_e32 v39, v39
	v_add_f32_e32 v119, 0, v32
	v_add_f32_e32 v119, v33, v119
	v_add_f32_e32 v119, v34, v119
	v_add_f32_e32 v119, v35, v119
	v_cvt_pk_bf16_f32 v32, v32, v33
	v_cvt_pk_bf16_f32 v33, v34, v35
	v_cvt_pk_bf16_f32 v34, v36, v37
	v_cvt_pk_bf16_f32 v35, v38, v39
	v_add_f32_e32 v119, v36, v119
	v_add_f32_e32 v119, v37, v119
	v_mfma_f32_32x32x16_bf16 v[16:31], v[124:127], v[32:35], v[16:31]
	v_add_f32_e32 v36, v38, v119
	v_exp_f32_e32 v40, v40
	v_exp_f32_e32 v41, v41
	v_add_f32_e32 v36, v39, v36
	v_exp_f32_e32 v37, v42
	v_exp_f32_e32 v38, v43
	v_exp_f32_e32 v39, v44
	s_waitcnt lgkmcnt(2)
	v_mfma_f32_32x32x16_bf16 v[0:15], v[128:131], v[32:35], v[0:15]
	v_exp_f32_e32 v42, v45
	v_exp_f32_e32 v43, v46
	v_exp_f32_e32 v44, v47
	v_add_f32_e32 v36, v40, v36
	v_cvt_pk_bf16_f32 v32, v40, v41
	v_cvt_pk_bf16_f32 v33, v37, v38
	v_cvt_pk_bf16_f32 v34, v39, v42
	v_cvt_pk_bf16_f32 v35, v43, v44
	v_add_f32_e32 v36, v41, v36
	v_add_f32_e32 v36, v37, v36
	s_waitcnt lgkmcnt(1)
	v_mfma_f32_32x32x16_bf16 v[16:31], v[120:123], v[32:35], v[16:31]
	v_add_f32_e32 v36, v38, v36
	v_add_f32_e32 v36, v39, v36
	v_add_f32_e32 v36, v42, v36
	v_add_f32_e32 v36, v43, v36
	v_add_f32_e32 v36, v44, v36
	v_add_f32_e32 v103, v103, v36
	s_waitcnt lgkmcnt(0)
	v_mfma_f32_32x32x16_bf16 v[0:15], v[132:135], v[32:35], v[0:15]
